# v18 plus hand-written final RMSNorm phase: next token loads in flight during normalise+store, norm weights loaded once
# speedup vs baseline: 1.0129x; 1.0002x over previous
; #define GDN_BAR() do { asm volatile("" ::: "memory"); __builtin_amdgcn_s_barrier(); asm volatile("" ::: "memory"); } while (0)
; DI void gdn_scan_prompt(const Params& p, int bh, unsigned char* smem) {
;     ...
;         }
;         if (wid >= 4) { if (n + 3 < 32) asm volatile("s_waitcnt vmcnt(18)" ::: "memory"); else asm volatile("s_waitcnt vmcnt(0)" ::: "memory"); }
;         else asm volatile("s_waitcnt lgkmcnt(0)" ::: "memory");
;         GDN_BAR();
.Lgs_body_end:
	s_mov_b64 s[90:91], -1
	s_and_b64 vcc, exec, s[22:23]
	s_cbranch_vccnz .LBB0_848

; DI void phase_final(const Params& p) {
;     const int lane = threadIdx.x & 63, gw = blockIdx.x * 8 + (threadIdx.x >> 6), nw = gridDim.x * 8;
;     const bf16_t* x2 = (const bf16_t*)(p.ws + WS_X2); const bf16_t* x1 = (const bf16_t*)(p.ws + WS_X1);
;     for (int tok = gw; tok < T_TOK; tok += nw) {
;         f32x4 v[4]; float ss = 0.f;
; #pragma unroll
;         for (int i = 0; i < 4; ++i) { const int c = 4 * lane + 256 * i;
.LBB0_1610:
	s_cmp_lt_i32 s80, 13
	s_cselect_b64 s[2:3], -1, 0
	s_and_b64 s[0:1], s[2:3], s[0:1]
	s_and_b64 s[0:1], s[44:45], s[0:1]
	s_and_saveexec_b64 s[2:3], s[0:1]
	s_cbranch_execz .LBB0_1629
	v_readlane_b32 s14, v238, 16
	v_readlane_b32 s15, v238, 17
	v_lshlrev_b32_e32 v2, 4, v196
	v_lshlrev_b32_e32 v3, 3, v196
	s_nop 3
	global_load_dwordx4 v[16:19], v2, s[14:15]
	global_load_dwordx4 v[20:23], v2, s[14:15] offset:1024
	global_load_dwordx4 v[24:27], v2, s[14:15] offset:2048
	global_load_dwordx4 v[28:31], v2, s[14:15] offset:3072
	v_readfirstlane_b32 s4, v162
	s_add_u32 s8, s78, 0x10880000
	s_addc_u32 s9, s79, 0
	s_mov_b32 s7, 0
	s_cmp_lt_u32 s4, 0x4000
	s_cbranch_scc0 .Lfin_sample
	s_lshl_b32 s5, s4, 11
	v_add_u32_e32 v4, s5, v3
	global_load_dwordx2 v[32:33], v4, s[8:9]
	global_load_dwordx2 v[34:35], v4, s[8:9] offset:512
	global_load_dwordx2 v[36:37], v4, s[8:9] offset:1024
	global_load_dwordx2 v[38:39], v4, s[8:9] offset:1536
	v_mov_b32_e32 v60, 0x358637bd
.Lfin_a:
	s_add_u32 s6, s4, s46
	s_cmp_lt_u32 s6, 0x4000
	s_cbranch_scc0 .Lfin_a_nonext
	s_lshl_b32 s5, s6, 11
	v_add_u32_e32 v5, s5, v3
	global_load_dwordx2 v[40:41], v5, s[8:9]
	global_load_dwordx2 v[42:43], v5, s[8:9] offset:512
	global_load_dwordx2 v[44:45], v5, s[8:9] offset:1024
	global_load_dwordx2 v[46:47], v5, s[8:9] offset:1536
	s_cmp_eq_u32 s7, 0
	s_cbranch_scc1 .Lfin_a_w4
	s_waitcnt vmcnt(8)
	s_branch .Lfin_a_have
.Lfin_a_w4:
	s_waitcnt vmcnt(4)
	s_branch .Lfin_a_have

; DI float bflo(unsigned u) { return __uint_as_float(u << 16); }
; DI float bfhi(unsigned u) { return __uint_as_float(u & 0xffff0000u); }
; DI void phase_final(const Params& p) {
;     ...
;             if (tok < T_PR) { const u32x2 t = *(const u32x2*)(x2 + (size_t)tok * 1024 + c); v[i] = (f32x4){bflo(t.x), bfhi(t.x), bflo(t.y), bfhi(t.y)}; }
;             else { const size_t o = (size_t)(tok - T_PR) * 1024 + c; const u32x2 t = *(const u32x2*)(x1 + (size_t)tok * 1024 + c); v[i] = (f32x4){bflo(t.x), bfhi(t.x), bflo(t.y), bfhi(t.y)};
; #pragma unroll
;                 for (int s = 0; s < 8; ++s) v[i] += *(const f32x4*)((const float*)(p.ws + WS_PART2) + (size_t)s * 1048576 + o); }
;             ss += v[i].x * v[i].x + v[i].y * v[i].y + v[i].z * v[i].z + v[i].w * v[i].w; }
;         ss = wave_sum(ss);
;         const float rstd = rsqrtf(ss * (1.f / 1024.f) + 1e-6f);
; #pragma unroll
;         for (int i = 0; i < 4; ++i) { const f32x4 ww = *(const f32x4*)(p.fnorm_w + 4 * lane + 256 * i);
;             *(f32x4*)(p.out + O_Y + (size_t)tok * 1024 + 4 * lane + 256 * i) = (f32x4){v[i].x * rstd * ww.x, v[i].y * rstd * ww.y, v[i].z * rstd * ww.z, v[i].w * rstd * ww.w}; }
.Lfin_a_have:
	s_mov_b32 s7, 1
	v_lshlrev_b32_e32 v64, 16, v32
	v_and_b32_e32 v65, 0xffff0000, v32
	v_lshlrev_b32_e32 v66, 16, v33
	v_and_b32_e32 v67, 0xffff0000, v33
	v_lshlrev_b32_e32 v68, 16, v34
	v_and_b32_e32 v69, 0xffff0000, v34
	v_lshlrev_b32_e32 v70, 16, v35
	v_and_b32_e32 v71, 0xffff0000, v35
	v_lshlrev_b32_e32 v72, 16, v36
	v_and_b32_e32 v73, 0xffff0000, v36
	v_lshlrev_b32_e32 v74, 16, v37
	v_and_b32_e32 v75, 0xffff0000, v37
	v_lshlrev_b32_e32 v76, 16, v38
	v_and_b32_e32 v77, 0xffff0000, v38
	v_lshlrev_b32_e32 v78, 16, v39
	v_and_b32_e32 v79, 0xffff0000, v39
	v_mul_f32_e32 v48, v64, v64
	v_fmac_f32_e32 v48, v65, v65
	v_fmac_f32_e32 v48, v66, v66
	v_fmac_f32_e32 v48, v67, v67
	v_mul_f32_e32 v49, v68, v68
	v_fmac_f32_e32 v49, v69, v69
	v_fmac_f32_e32 v49, v70, v70
	v_fmac_f32_e32 v49, v71, v71
	v_mul_f32_e32 v50, v72, v72
	v_fmac_f32_e32 v50, v73, v73
	v_fmac_f32_e32 v50, v74, v74
	v_fmac_f32_e32 v50, v75, v75
	v_mul_f32_e32 v51, v76, v76
	v_fmac_f32_e32 v51, v77, v77
	v_fmac_f32_e32 v51, v78, v78
	v_fmac_f32_e32 v51, v79, v79
	v_add_f32_e32 v48, v48, v49
	v_add_f32_e32 v50, v50, v51
	v_add_f32_e32 v48, v48, v50
	s_nop 1
	v_add_f32_dpp v48, v48, v48 quad_perm:[1,0,3,2] row_mask:0xf bank_mask:0xf bound_ctrl:1
	s_nop 1
	v_add_f32_dpp v48, v48, v48 quad_perm:[2,3,0,1] row_mask:0xf bank_mask:0xf bound_ctrl:1
	s_nop 1
	v_add_f32_dpp v48, v48, v48 row_ror:4 row_mask:0xf bank_mask:0xf bound_ctrl:1
	s_nop 1
	v_add_f32_dpp v48, v48, v48 row_ror:8 row_mask:0xf bank_mask:0xf bound_ctrl:1
	s_nop 1
	v_readlane_b32 s16, v48, 0
	v_readlane_b32 s17, v48, 16
	v_readlane_b32 s18, v48, 32
	v_readlane_b32 s19, v48, 48
	s_nop 1
	v_mov_b32_e32 v52, s16
	v_add_f32_e32 v52, s17, v52
	v_add_f32_e32 v52, s18, v52
	v_add_f32_e32 v52, s19, v52
	v_fmamk_f32 v52, v52, 0x3a800000, v60
	v_rsq_f32_e32 v52, v52
	s_mov_b32 s11, 0
	s_lshl_b32 s10, s4, 12
	s_add_u32 s10, s76, s10
	s_addc_u32 s11, s77, 0
	v_mul_f32_e32 v64, v64, v52
	v_mul_f32_e32 v65, v65, v52
	v_mul_f32_e32 v66, v66, v52
	v_mul_f32_e32 v67, v67, v52
	v_mul_f32_e32 v64, v64, v16
	v_mul_f32_e32 v65, v65, v17
	v_mul_f32_e32 v66, v66, v18
	v_mul_f32_e32 v67, v67, v19
	global_store_dwordx4 v2, v[64:67], s[10:11]
	v_mul_f32_e32 v68, v68, v52
	v_mul_f32_e32 v69, v69, v52
	v_mul_f32_e32 v70, v70, v52
	v_mul_f32_e32 v71, v71, v52
	v_mul_f32_e32 v68, v68, v20
	v_mul_f32_e32 v69, v69, v21
	v_mul_f32_e32 v70, v70, v22
	v_mul_f32_e32 v71, v71, v23
	global_store_dwordx4 v2, v[68:71], s[10:11] offset:1024
	v_mul_f32_e32 v72, v72, v52
	v_mul_f32_e32 v73, v73, v52
	v_mul_f32_e32 v74, v74, v52
	v_mul_f32_e32 v75, v75, v52
	v_mul_f32_e32 v72, v72, v24
	v_mul_f32_e32 v73, v73, v25
	v_mul_f32_e32 v74, v74, v26
	v_mul_f32_e32 v75, v75, v27
	global_store_dwordx4 v2, v[72:75], s[10:11] offset:2048
	v_mul_f32_e32 v76, v76, v52
	v_mul_f32_e32 v77, v77, v52
	v_mul_f32_e32 v78, v78, v52
	v_mul_f32_e32 v79, v79, v52
	v_mul_f32_e32 v76, v76, v28
	v_mul_f32_e32 v77, v77, v29
	v_mul_f32_e32 v78, v78, v30
	v_mul_f32_e32 v79, v79, v31
	global_store_dwordx4 v2, v[76:79], s[10:11] offset:3072
	s_mov_b32 s4, s6
	s_cmp_lt_u32 s4, 0x4000
	s_cbranch_scc0 .Lfin_sample
.Lfin_b:
	s_add_u32 s6, s4, s46
	s_cmp_lt_u32 s6, 0x4000
	s_cbranch_scc0 .Lfin_b_nonext
	s_lshl_b32 s5, s6, 11
	v_add_u32_e32 v5, s5, v3
	global_load_dwordx2 v[32:33], v5, s[8:9]
	global_load_dwordx2 v[34:35], v5, s[8:9] offset:512
	global_load_dwordx2 v[36:37], v5, s[8:9] offset:1024
	global_load_dwordx2 v[38:39], v5, s[8:9] offset:1536
	s_cmp_eq_u32 s7, 0
	s_cbranch_scc1 .Lfin_b_w4
	s_waitcnt vmcnt(8)
	s_branch .Lfin_b_have

; DI float bflo(unsigned u) { return __uint_as_float(u << 16); }
; DI float bfhi(unsigned u) { return __uint_as_float(u & 0xffff0000u); }
; DI void phase_final(const Params& p) {
;     ...
;     for (int tok = gw; tok < T_TOK; tok += nw) {
;         f32x4 v[4]; float ss = 0.f;
; #pragma unroll
;         for (int i = 0; i < 4; ++i) { const int c = 4 * lane + 256 * i;
;             if (tok < T_PR) { const u32x2 t = *(const u32x2*)(x2 + (size_t)tok * 1024 + c); v[i] = (f32x4){bflo(t.x), bfhi(t.x), bflo(t.y), bfhi(t.y)}; }
;             else { const size_t o = (size_t)(tok - T_PR) * 1024 + c; const u32x2 t = *(const u32x2*)(x1 + (size_t)tok * 1024 + c); v[i] = (f32x4){bflo(t.x), bfhi(t.x), bflo(t.y), bfhi(t.y)};
; #pragma unroll
;                 for (int s = 0; s < 8; ++s) v[i] += *(const f32x4*)((const float*)(p.ws + WS_PART2) + (size_t)s * 1048576 + o); }
;             ss += v[i].x * v[i].x + v[i].y * v[i].y + v[i].z * v[i].z + v[i].w * v[i].w; }
;         ss = wave_sum(ss);
;         const float rstd = rsqrtf(ss * (1.f / 1024.f) + 1e-6f);
; #pragma unroll
;         for (int i = 0; i < 4; ++i) { const f32x4 ww = *(const f32x4*)(p.fnorm_w + 4 * lane + 256 * i);
;             *(f32x4*)(p.out + O_Y + (size_t)tok * 1024 + 4 * lane + 256 * i) = (f32x4){v[i].x * rstd * ww.x, v[i].y * rstd * ww.y, v[i].z * rstd * ww.z, v[i].w * rstd * ww.w}; }
.Lfin_b_have:
	s_mov_b32 s7, 1
	v_lshlrev_b32_e32 v64, 16, v40
	v_and_b32_e32 v65, 0xffff0000, v40
	v_lshlrev_b32_e32 v66, 16, v41
	v_and_b32_e32 v67, 0xffff0000, v41
	v_lshlrev_b32_e32 v68, 16, v42
	v_and_b32_e32 v69, 0xffff0000, v42
	v_lshlrev_b32_e32 v70, 16, v43
	v_and_b32_e32 v71, 0xffff0000, v43
	v_lshlrev_b32_e32 v72, 16, v44
	v_and_b32_e32 v73, 0xffff0000, v44
	v_lshlrev_b32_e32 v74, 16, v45
	v_and_b32_e32 v75, 0xffff0000, v45
	v_lshlrev_b32_e32 v76, 16, v46
	v_and_b32_e32 v77, 0xffff0000, v46
	v_lshlrev_b32_e32 v78, 16, v47
	v_and_b32_e32 v79, 0xffff0000, v47
	v_mul_f32_e32 v48, v64, v64
	v_fmac_f32_e32 v48, v65, v65
	v_fmac_f32_e32 v48, v66, v66
	v_fmac_f32_e32 v48, v67, v67
	v_mul_f32_e32 v49, v68, v68
	v_fmac_f32_e32 v49, v69, v69
	v_fmac_f32_e32 v49, v70, v70
	v_fmac_f32_e32 v49, v71, v71
	v_mul_f32_e32 v50, v72, v72
	v_fmac_f32_e32 v50, v73, v73
	v_fmac_f32_e32 v50, v74, v74
	v_fmac_f32_e32 v50, v75, v75
	v_mul_f32_e32 v51, v76, v76
	v_fmac_f32_e32 v51, v77, v77
	v_fmac_f32_e32 v51, v78, v78
	v_fmac_f32_e32 v51, v79, v79
	v_add_f32_e32 v48, v48, v49
	v_add_f32_e32 v50, v50, v51
	v_add_f32_e32 v48, v48, v50
	s_nop 1
	v_add_f32_dpp v48, v48, v48 quad_perm:[1,0,3,2] row_mask:0xf bank_mask:0xf bound_ctrl:1
	s_nop 1
	v_add_f32_dpp v48, v48, v48 quad_perm:[2,3,0,1] row_mask:0xf bank_mask:0xf bound_ctrl:1
	s_nop 1
	v_add_f32_dpp v48, v48, v48 row_ror:4 row_mask:0xf bank_mask:0xf bound_ctrl:1
	s_nop 1
	v_add_f32_dpp v48, v48, v48 row_ror:8 row_mask:0xf bank_mask:0xf bound_ctrl:1
	s_nop 1
	v_readlane_b32 s16, v48, 0
	v_readlane_b32 s17, v48, 16
	v_readlane_b32 s18, v48, 32
	v_readlane_b32 s19, v48, 48
	s_nop 1
	v_mov_b32_e32 v52, s16
	v_add_f32_e32 v52, s17, v52
	v_add_f32_e32 v52, s18, v52
	v_add_f32_e32 v52, s19, v52
	v_fmamk_f32 v52, v52, 0x3a800000, v60
	v_rsq_f32_e32 v52, v52
	s_mov_b32 s11, 0
	s_lshl_b32 s10, s4, 12
	s_add_u32 s10, s76, s10
	s_addc_u32 s11, s77, 0
	v_mul_f32_e32 v64, v64, v52
	v_mul_f32_e32 v65, v65, v52
	v_mul_f32_e32 v66, v66, v52
	v_mul_f32_e32 v67, v67, v52
	v_mul_f32_e32 v64, v64, v16
	v_mul_f32_e32 v65, v65, v17
	v_mul_f32_e32 v66, v66, v18
	v_mul_f32_e32 v67, v67, v19
	global_store_dwordx4 v2, v[64:67], s[10:11]
	v_mul_f32_e32 v68, v68, v52
	v_mul_f32_e32 v69, v69, v52
	v_mul_f32_e32 v70, v70, v52
	v_mul_f32_e32 v71, v71, v52
	v_mul_f32_e32 v68, v68, v20
	v_mul_f32_e32 v69, v69, v21
	v_mul_f32_e32 v70, v70, v22
	v_mul_f32_e32 v71, v71, v23
	global_store_dwordx4 v2, v[68:71], s[10:11] offset:1024
	v_mul_f32_e32 v72, v72, v52
	v_mul_f32_e32 v73, v73, v52
	v_mul_f32_e32 v74, v74, v52
	v_mul_f32_e32 v75, v75, v52
	v_mul_f32_e32 v72, v72, v24
	v_mul_f32_e32 v73, v73, v25
	v_mul_f32_e32 v74, v74, v26
	v_mul_f32_e32 v75, v75, v27
	global_store_dwordx4 v2, v[72:75], s[10:11] offset:2048
	v_mul_f32_e32 v76, v76, v52
	v_mul_f32_e32 v77, v77, v52
	v_mul_f32_e32 v78, v78, v52
	v_mul_f32_e32 v79, v79, v52
	v_mul_f32_e32 v76, v76, v28
	v_mul_f32_e32 v77, v77, v29
	v_mul_f32_e32 v78, v78, v30
	v_mul_f32_e32 v79, v79, v31
	global_store_dwordx4 v2, v[76:79], s[10:11] offset:3072
	s_mov_b32 s4, s6
	s_cmp_lt_u32 s4, 0x4000
	s_cbranch_scc1 .Lfin_a
.Lfin_sample:
	s_cmp_lt_u32 s4, 0x4400
	s_cbranch_scc0 .Lfin_done
	v_mov_b32_e32 v60, 0x358637bd
	s_add_u32 s8, s78, 0xc480000
	s_addc_u32 s9, s79, 0
	s_lshl_b32 s5, s4, 11
	v_add_u32_e32 v4, s5, v3
	global_load_dwordx2 v[32:33], v4, s[8:9]
	global_load_dwordx2 v[34:35], v4, s[8:9] offset:512
	global_load_dwordx2 v[36:37], v4, s[8:9] offset:1024
	global_load_dwordx2 v[38:39], v4, s[8:9] offset:1536
	s_sub_u32 s5, s4, 0x4000
	s_lshl_b32 s5, s5, 12
	s_add_u32 s12, s78, 0x14c80000
	s_addc_u32 s13, s79, 0
	s_add_u32 s12, s12, s5
	s_addc_u32 s13, s13, 0
	global_load_dwordx4 v[80:83], v2, s[12:13]
	global_load_dwordx4 v[84:87], v2, s[12:13] offset:1024
	global_load_dwordx4 v[88:91], v2, s[12:13] offset:2048
	global_load_dwordx4 v[92:95], v2, s[12:13] offset:3072
	s_add_u32 s12, s12, 0x400000
	s_addc_u32 s13, s13, 0
	global_load_dwordx4 v[96:99], v2, s[12:13]
	global_load_dwordx4 v[100:103], v2, s[12:13] offset:1024
	global_load_dwordx4 v[104:107], v2, s[12:13] offset:2048
	global_load_dwordx4 v[108:111], v2, s[12:13] offset:3072
	s_add_u32 s12, s12, 0x400000
	s_addc_u32 s13, s13, 0
	global_load_dwordx4 v[112:115], v2, s[12:13]
	global_load_dwordx4 v[116:119], v2, s[12:13] offset:1024
	global_load_dwordx4 v[120:123], v2, s[12:13] offset:2048
	global_load_dwordx4 v[124:127], v2, s[12:13] offset:3072
	s_add_u32 s12, s12, 0x400000
	s_addc_u32 s13, s13, 0
	global_load_dwordx4 v[128:131], v2, s[12:13]
	global_load_dwordx4 v[132:135], v2, s[12:13] offset:1024
	global_load_dwordx4 v[136:139], v2, s[12:13] offset:2048
	global_load_dwordx4 v[140:143], v2, s[12:13] offset:3072
	s_add_u32 s12, s12, 0x400000
	s_addc_u32 s13, s13, 0
	global_load_dwordx4 v[144:147], v2, s[12:13]
	global_load_dwordx4 v[148:151], v2, s[12:13] offset:1024
	global_load_dwordx4 v[152:155], v2, s[12:13] offset:2048
	global_load_dwordx4 v[156:159], v2, s[12:13] offset:3072
	s_add_u32 s12, s12, 0x400000
	s_addc_u32 s13, s13, 0
	global_load_dwordx4 v[160:163], v2, s[12:13]
	global_load_dwordx4 v[164:167], v2, s[12:13] offset:1024
	global_load_dwordx4 v[168:171], v2, s[12:13] offset:2048
	global_load_dwordx4 v[172:175], v2, s[12:13] offset:3072
	s_add_u32 s12, s12, 0x400000
	s_addc_u32 s13, s13, 0
	global_load_dwordx4 v[176:179], v2, s[12:13]
	global_load_dwordx4 v[180:183], v2, s[12:13] offset:1024
	global_load_dwordx4 v[184:187], v2, s[12:13] offset:2048
	global_load_dwordx4 v[188:191], v2, s[12:13] offset:3072
	s_add_u32 s12, s12, 0x400000
	s_addc_u32 s13, s13, 0
	global_load_dwordx4 v[192:195], v2, s[12:13]
	global_load_dwordx4 v[196:199], v2, s[12:13] offset:1024
	global_load_dwordx4 v[200:203], v2, s[12:13] offset:2048
	global_load_dwordx4 v[204:207], v2, s[12:13] offset:3072
	s_waitcnt vmcnt(0)
; DI float bflo(unsigned u) { return __uint_as_float(u << 16); }
; DI float bfhi(unsigned u) { return __uint_as_float(u & 0xffff0000u); }
; DI void phase_final(const Params& p) {
;     ...
;             if (tok < T_PR) { const u32x2 t = *(const u32x2*)(x2 + (size_t)tok * 1024 + c); v[i] = (f32x4){bflo(t.x), bfhi(t.x), bflo(t.y), bfhi(t.y)}; }
;             else { const size_t o = (size_t)(tok - T_PR) * 1024 + c; const u32x2 t = *(const u32x2*)(x1 + (size_t)tok * 1024 + c); v[i] = (f32x4){bflo(t.x), bfhi(t.x), bflo(t.y), bfhi(t.y)};
; #pragma unroll
;                 for (int s = 0; s < 8; ++s) v[i] += *(const f32x4*)((const float*)(p.ws + WS_PART2) + (size_t)s * 1048576 + o); }
;             ss += v[i].x * v[i].x + v[i].y * v[i].y + v[i].z * v[i].z + v[i].w * v[i].w; }
;         ss = wave_sum(ss);
;         const float rstd = rsqrtf(ss * (1.f / 1024.f) + 1e-6f);
; #pragma unroll
;         for (int i = 0; i < 4; ++i) { const f32x4 ww = *(const f32x4*)(p.fnorm_w + 4 * lane + 256 * i);
;             *(f32x4*)(p.out + O_Y + (size_t)tok * 1024 + 4 * lane + 256 * i) = (f32x4){v[i].x * rstd * ww.x, v[i].y * rstd * ww.y, v[i].z * rstd * ww.z, v[i].w * rstd * ww.w}; }
	v_lshlrev_b32_e32 v64, 16, v32
	v_and_b32_e32 v65, 0xffff0000, v32
	v_lshlrev_b32_e32 v66, 16, v33
	v_and_b32_e32 v67, 0xffff0000, v33
	v_lshlrev_b32_e32 v68, 16, v34
	v_and_b32_e32 v69, 0xffff0000, v34
	v_lshlrev_b32_e32 v70, 16, v35
	v_and_b32_e32 v71, 0xffff0000, v35
	v_lshlrev_b32_e32 v72, 16, v36
	v_and_b32_e32 v73, 0xffff0000, v36
	v_lshlrev_b32_e32 v74, 16, v37
	v_and_b32_e32 v75, 0xffff0000, v37
	v_lshlrev_b32_e32 v76, 16, v38
	v_and_b32_e32 v77, 0xffff0000, v38
	v_lshlrev_b32_e32 v78, 16, v39
	v_and_b32_e32 v79, 0xffff0000, v39
	v_add_f32_e32 v64, v64, v80
	v_add_f32_e32 v65, v65, v81
	v_add_f32_e32 v66, v66, v82
	v_add_f32_e32 v67, v67, v83
	v_add_f32_e32 v68, v68, v84
	v_add_f32_e32 v69, v69, v85
	v_add_f32_e32 v70, v70, v86
	v_add_f32_e32 v71, v71, v87
	v_add_f32_e32 v72, v72, v88
	v_add_f32_e32 v73, v73, v89
	v_add_f32_e32 v74, v74, v90
	v_add_f32_e32 v75, v75, v91
	v_add_f32_e32 v76, v76, v92
	v_add_f32_e32 v77, v77, v93
	v_add_f32_e32 v78, v78, v94
	v_add_f32_e32 v79, v79, v95
	v_add_f32_e32 v64, v64, v96
	v_add_f32_e32 v65, v65, v97
	v_add_f32_e32 v66, v66, v98
	v_add_f32_e32 v67, v67, v99
	v_add_f32_e32 v68, v68, v100
	v_add_f32_e32 v69, v69, v101
	v_add_f32_e32 v70, v70, v102
	v_add_f32_e32 v71, v71, v103
	v_add_f32_e32 v72, v72, v104
	v_add_f32_e32 v73, v73, v105
	v_add_f32_e32 v74, v74, v106
	v_add_f32_e32 v75, v75, v107
	v_add_f32_e32 v76, v76, v108
	v_add_f32_e32 v77, v77, v109
	v_add_f32_e32 v78, v78, v110
	v_add_f32_e32 v79, v79, v111
	v_add_f32_e32 v64, v64, v112
	v_add_f32_e32 v65, v65, v113
	v_add_f32_e32 v66, v66, v114
	v_add_f32_e32 v67, v67, v115
	v_add_f32_e32 v68, v68, v116
	v_add_f32_e32 v69, v69, v117
	v_add_f32_e32 v70, v70, v118
	v_add_f32_e32 v71, v71, v119
	v_add_f32_e32 v72, v72, v120
	v_add_f32_e32 v73, v73, v121
	v_add_f32_e32 v74, v74, v122
	v_add_f32_e32 v75, v75, v123
	v_add_f32_e32 v76, v76, v124
	v_add_f32_e32 v77, v77, v125
	v_add_f32_e32 v78, v78, v126
	v_add_f32_e32 v79, v79, v127
	v_add_f32_e32 v64, v64, v128
	v_add_f32_e32 v65, v65, v129
	v_add_f32_e32 v66, v66, v130
	v_add_f32_e32 v67, v67, v131
	v_add_f32_e32 v68, v68, v132
	v_add_f32_e32 v69, v69, v133
	v_add_f32_e32 v70, v70, v134
	v_add_f32_e32 v71, v71, v135
	v_add_f32_e32 v72, v72, v136
	v_add_f32_e32 v73, v73, v137
	v_add_f32_e32 v74, v74, v138
	v_add_f32_e32 v75, v75, v139
	v_add_f32_e32 v76, v76, v140
	v_add_f32_e32 v77, v77, v141
	v_add_f32_e32 v78, v78, v142
	v_add_f32_e32 v79, v79, v143
	v_add_f32_e32 v64, v64, v144
	v_add_f32_e32 v65, v65, v145
	v_add_f32_e32 v66, v66, v146
	v_add_f32_e32 v67, v67, v147
	v_add_f32_e32 v68, v68, v148
	v_add_f32_e32 v69, v69, v149
	v_add_f32_e32 v70, v70, v150
	v_add_f32_e32 v71, v71, v151
	v_add_f32_e32 v72, v72, v152
	v_add_f32_e32 v73, v73, v153
	v_add_f32_e32 v74, v74, v154
	v_add_f32_e32 v75, v75, v155
	v_add_f32_e32 v76, v76, v156
	v_add_f32_e32 v77, v77, v157
	v_add_f32_e32 v78, v78, v158
	v_add_f32_e32 v79, v79, v159
	v_add_f32_e32 v64, v64, v160
	v_add_f32_e32 v65, v65, v161
	v_add_f32_e32 v66, v66, v162
	v_add_f32_e32 v67, v67, v163
	v_add_f32_e32 v68, v68, v164
	v_add_f32_e32 v69, v69, v165
	v_add_f32_e32 v70, v70, v166
	v_add_f32_e32 v71, v71, v167
	v_add_f32_e32 v72, v72, v168
	v_add_f32_e32 v73, v73, v169
	v_add_f32_e32 v74, v74, v170
	v_add_f32_e32 v75, v75, v171
	v_add_f32_e32 v76, v76, v172
	v_add_f32_e32 v77, v77, v173
	v_add_f32_e32 v78, v78, v174
	v_add_f32_e32 v79, v79, v175
	v_add_f32_e32 v64, v64, v176
	v_add_f32_e32 v65, v65, v177
	v_add_f32_e32 v66, v66, v178
	v_add_f32_e32 v67, v67, v179
	v_add_f32_e32 v68, v68, v180
	v_add_f32_e32 v69, v69, v181
	v_add_f32_e32 v70, v70, v182
	v_add_f32_e32 v71, v71, v183
	v_add_f32_e32 v72, v72, v184
	v_add_f32_e32 v73, v73, v185
	v_add_f32_e32 v74, v74, v186
	v_add_f32_e32 v75, v75, v187
	v_add_f32_e32 v76, v76, v188
	v_add_f32_e32 v77, v77, v189
	v_add_f32_e32 v78, v78, v190
	v_add_f32_e32 v79, v79, v191
	v_add_f32_e32 v64, v64, v192
	v_add_f32_e32 v65, v65, v193
	v_add_f32_e32 v66, v66, v194
	v_add_f32_e32 v67, v67, v195
	v_add_f32_e32 v68, v68, v196
	v_add_f32_e32 v69, v69, v197
	v_add_f32_e32 v70, v70, v198
	v_add_f32_e32 v71, v71, v199
	v_add_f32_e32 v72, v72, v200
	v_add_f32_e32 v73, v73, v201
	v_add_f32_e32 v74, v74, v202
	v_add_f32_e32 v75, v75, v203
	v_add_f32_e32 v76, v76, v204
	v_add_f32_e32 v77, v77, v205
	v_add_f32_e32 v78, v78, v206
	v_add_f32_e32 v79, v79, v207
	v_mul_f32_e32 v48, v64, v64
	v_fmac_f32_e32 v48, v65, v65
	v_fmac_f32_e32 v48, v66, v66
	v_fmac_f32_e32 v48, v67, v67
	v_mul_f32_e32 v49, v68, v68
	v_fmac_f32_e32 v49, v69, v69
	v_fmac_f32_e32 v49, v70, v70
	v_fmac_f32_e32 v49, v71, v71
	v_mul_f32_e32 v50, v72, v72
	v_fmac_f32_e32 v50, v73, v73
	v_fmac_f32_e32 v50, v74, v74
	v_fmac_f32_e32 v50, v75, v75
	v_mul_f32_e32 v51, v76, v76
	v_fmac_f32_e32 v51, v77, v77
	v_fmac_f32_e32 v51, v78, v78
	v_fmac_f32_e32 v51, v79, v79
	v_add_f32_e32 v48, v48, v49
	v_add_f32_e32 v50, v50, v51
	v_add_f32_e32 v48, v48, v50
	s_nop 1
	v_add_f32_dpp v48, v48, v48 quad_perm:[1,0,3,2] row_mask:0xf bank_mask:0xf bound_ctrl:1
	s_nop 1
	v_add_f32_dpp v48, v48, v48 quad_perm:[2,3,0,1] row_mask:0xf bank_mask:0xf bound_ctrl:1
	s_nop 1
	v_add_f32_dpp v48, v48, v48 row_ror:4 row_mask:0xf bank_mask:0xf bound_ctrl:1
	s_nop 1
	v_add_f32_dpp v48, v48, v48 row_ror:8 row_mask:0xf bank_mask:0xf bound_ctrl:1
	s_nop 1
	v_readlane_b32 s16, v48, 0
	v_readlane_b32 s17, v48, 16
	v_readlane_b32 s18, v48, 32
	v_readlane_b32 s19, v48, 48
	s_nop 1
	v_mov_b32_e32 v52, s16
	v_add_f32_e32 v52, s17, v52
	v_add_f32_e32 v52, s18, v52
	v_add_f32_e32 v52, s19, v52
	v_fmamk_f32 v52, v52, 0x3a800000, v60
	v_rsq_f32_e32 v52, v52
	s_mov_b32 s11, 0
	s_lshl_b32 s10, s4, 12
	s_add_u32 s10, s76, s10
	s_addc_u32 s11, s77, 0
	v_mul_f32_e32 v64, v64, v52
	v_mul_f32_e32 v65, v65, v52
	v_mul_f32_e32 v66, v66, v52
	v_mul_f32_e32 v67, v67, v52
	v_mul_f32_e32 v64, v64, v16
	v_mul_f32_e32 v65, v65, v17
	v_mul_f32_e32 v66, v66, v18
	v_mul_f32_e32 v67, v67, v19
	global_store_dwordx4 v2, v[64:67], s[10:11]
	v_mul_f32_e32 v68, v68, v52
	v_mul_f32_e32 v69, v69, v52
	v_mul_f32_e32 v70, v70, v52
	v_mul_f32_e32 v71, v71, v52
	v_mul_f32_e32 v68, v68, v20
	v_mul_f32_e32 v69, v69, v21
	v_mul_f32_e32 v70, v70, v22
	v_mul_f32_e32 v71, v71, v23
	global_store_dwordx4 v2, v[68:71], s[10:11] offset:1024
	v_mul_f32_e32 v72, v72, v52
	v_mul_f32_e32 v73, v73, v52
	v_mul_f32_e32 v74, v74, v52
	v_mul_f32_e32 v75, v75, v52
	v_mul_f32_e32 v72, v72, v24
	v_mul_f32_e32 v73, v73, v25
	v_mul_f32_e32 v74, v74, v26
	v_mul_f32_e32 v75, v75, v27
	global_store_dwordx4 v2, v[72:75], s[10:11] offset:2048
	v_mul_f32_e32 v76, v76, v52
	v_mul_f32_e32 v77, v77, v52
	v_mul_f32_e32 v78, v78, v52
	v_mul_f32_e32 v79, v79, v52
	v_mul_f32_e32 v76, v76, v28
	v_mul_f32_e32 v77, v77, v29
	v_mul_f32_e32 v78, v78, v30
	v_mul_f32_e32 v79, v79, v31
	global_store_dwordx4 v2, v[76:79], s[10:11] offset:3072
.Lfin_done:
.LBB0_1629:
	s_endpgm
